# SEAM(2) relaxed: all workgroups arrive (one L2 write-back per XCD), only the 32 scan workgroups wait; attention starts without a grid barrier; in-phase barrier before gated norm is a counter wait
# speedup vs baseline: 1.2900x; 1.0158x over previous
.LBB0_524:
	v_readlane_b32 s4, v233, 2
	v_readlane_b32 s5, v233, 3
	v_readlane_b32 s6, v233, 4
	v_readlane_b32 s7, v233, 5
	s_cmp_gt_i32 s5, 3
	s_cselect_b64 s[6:7], -1, 0
	s_and_b64 s[4:5], s[46:47], s[6:7]
	s_andn2_b64 vcc, exec, s[4:5]
	s_cbranch_vccnz .LBB0_578
	s_waitcnt vmcnt(0)
	v_readlane_b32 s0, v233, 9
	v_readlane_b32 s1, v233, 10
	s_waitcnt vmcnt(0)
	s_barrier
	s_and_saveexec_b64 s[8:9], s[0:1]
	s_cbranch_execz .LBB0_577
	v_readlane_b32 s3, v233, 8
	s_lshl_b32 s3, s3, 6
	s_add_i32 s3, s3, 0xc100
	v_mov_b32_e32 v0, s3
	v_mov_b32_e32 v1, 1
	global_atomic_add v2, v0, v1, s[48:49] sc0
	v_mov_b32_e32 v3, 0x25fc0
	ds_read_b32 v3, v3
	s_waitcnt vmcnt(0) lgkmcnt(0)
	v_add_u32_e32 v2, 1, v2
	v_cmp_eq_u32_e32 vcc, v2, v3
	s_cbranch_vccz .LBB0_577
	buffer_wbl2 sc1
	s_waitcnt vmcnt(0)
	v_mov_b32_e32 v0, 0xc600
	global_atomic_add v0, v1, s[48:49]
	s_waitcnt vmcnt(0)

.LBB0_582:
	v_cmp_eq_u32_e32 vcc, 0, v188
	s_and_saveexec_b64 s[4:5], vcc
	s_cbranch_execz .Ls2_wait_done
	v_mov_b32_e32 v0, 0x25fc4
	ds_read_b32 v0, v0
	v_mov_b32_e32 v1, 0xc600
	s_waitcnt lgkmcnt(0)
	v_readfirstlane_b32 s16, v0
	s_mov_b32 s3, 0
.Ls2_wait:
	global_load_dword v2, v1, s[48:49] sc1
	s_waitcnt vmcnt(0)
	v_readfirstlane_b32 s0, v2
	s_add_u32 s3, s3, 1
	s_nop 3
	s_cmp_ge_u32 s0, s16
	s_cbranch_scc1 .Ls2_ready
	s_sleep 1
	s_cmp_lt_u32 s3, 0x40000
	s_cbranch_scc1 .Ls2_wait

.Ls2_wait_done:
	s_or_b64 exec, exec, s[4:5]
	s_barrier
	s_mov_b32 s3, 0
	s_lshl_b64 s[54:55], s[2:3], 19
	s_add_u32 s7, s34, s54
	s_addc_u32 s16, s35, s55
	s_lshl_b32 s6, s2, 20
	s_mul_i32 s71, s2, 0x1c0000
	s_lshl_b32 s4, s2, 5
	s_and_b32 s0, s6, 0x1c00000
	s_mul_hi_u32 s70, s2, 0x1c0000
	s_mov_b32 s5, s3
	s_add_u32 s17, s30, s71
	s_addc_u32 s18, s31, s70
	s_lshl_b64 s[4:5], s[4:5], 2
	s_add_u32 s4, s48, s4
	s_addc_u32 s5, s49, s5
	s_lshl_b32 s6, s44, 10
	v_lshlrev_b32_e32 v48, 2, v56
	v_mov_b32_e32 v49, 0
	s_add_i32 s72, s6, 0xffff2000
	v_lshl_add_u64 v[0:1], s[4:5], 0, v[48:49]
	s_add_u32 s5, s7, s72
	s_addc_u32 s20, s16, 0
	s_ashr_i32 s65, s6, 31
	s_add_u32 s21, s17, s6
	s_addc_u32 s22, s18, s65
	s_add_i32 s56, s6, 0x2000
	s_add_i32 s23, s6, 0
	s_ashr_i32 s64, s56, 31
	s_add_u32 s26, s17, s56
	s_addc_u32 s27, s18, s64
	s_add_i32 s74, s6, 0xffff4000
	s_add_u32 s36, s7, s74
	s_addc_u32 s37, s16, 0
	s_add_i32 s66, s6, 0x4000
	s_add_i32 s38, s23, 0x2000
	s_ashr_i32 s67, s66, 31
	s_add_u32 s39, s17, s66
	s_addc_u32 s42, s18, s67
	s_add_i32 s78, s6, 0xffff6000
	s_add_u32 s43, s7, s78
	s_addc_u32 s50, s16, 0
	s_add_i32 s68, s6, 0x6000
	s_add_i32 s51, s23, 0x4000
	s_ashr_i32 s69, s68, 31
	s_add_u32 s57, s17, s68
	s_addc_u32 s89, s18, s69
	s_add_i32 s80, s6, 0xffff8000
	s_mov_b32 s4, 0x1d0000
	s_add_u32 s91, s7, s80
	v_add_co_u32_e32 v0, vcc, s4, v0
	s_addc_u32 s96, s16, 0
	s_add_i32 s73, s6, 0x8000
	v_addc_co_u32_e32 v1, vcc, 0, v1, vcc
	s_add_i32 s97, s23, 0x6000
	s_ashr_i32 s75, s73, 31
	s_add_u32 vcc_lo, s17, s73
	s_addc_u32 vcc_hi, s18, s75
	s_add_i32 s82, s6, 0xffffa000
	s_add_u32 s76, s7, s82
	s_mov_b32 s90, s44
	s_addc_u32 s44, s16, 0
	s_add_i32 s79, s6, 0xa000
	s_add_i32 s45, s23, 0x8000
	s_ashr_i32 s81, s79, 31
	s_add_u32 s87, s17, s79
	s_addc_u32 s46, s18, s81
	s_add_i32 s84, s6, 0xffffc000
	s_add_u32 s47, s7, s84
	s_addc_u32 s86, s16, 0
	s_add_i32 s83, s6, 0xc000
	v_writelane_b32 v233, s52, 36
	s_add_i32 s8, s23, 0xa000
	s_ashr_i32 s85, s83, 31
	v_writelane_b32 v233, s53, 37
	s_add_u32 s9, s17, s83
	v_writelane_b32 v233, s0, 38
	s_addc_u32 s0, s18, s85
	s_add_i32 s88, s6, 0xffffe000
	s_add_u32 s1, s7, s88
	s_addc_u32 s52, s16, 0
	s_add_i32 s53, s23, 0xc000
	s_add_u32 s58, s7, s6
	s_addc_u32 s59, s16, 0
	s_add_i32 s14, s23, 0xe000
	s_add_i32 s4, s6, 0x10000
	s_add_u32 s60, s7, s56
	s_addc_u32 s61, s16, 0
	s_add_i32 s15, s23, 0x10000
	s_add_u32 s12, s7, 0x4000
	s_addc_u32 s13, s16, 0
	s_add_u32 s7, s17, 0xe000
	s_addc_u32 s24, s18, 0
	s_add_u32 s25, s7, s6
	s_addc_u32 s62, s24, s65
	s_add_u32 s92, s12, s72
	s_addc_u32 s63, s13, 0
	s_cmpk_lt_u32 s33, 0xe00
	s_cselect_b64 s[16:17], -1, 0
	s_and_b64 s[18:19], s[16:17], exec
	s_cselect_b32 s19, s22, s20
	s_cselect_b32 s18, s21, s5
	s_cselect_b32 s63, s62, s63
	s_cselect_b32 s62, s25, s92
	s_add_i32 s5, 0, 0x12000
	s_add_i32 s25, s5, s6
	s_add_u32 s22, s7, s56
	s_mov_b32 m0, s23
	s_addc_u32 s23, s24, s64
	s_add_u32 s92, s12, s74
	s_addc_u32 s93, s13, 0
	v_lshlrev_b32_e32 v48, 4, v218
	s_cmpk_lt_u32 s33, 0xc00
	global_load_lds_dwordx4 v48, s[18:19]
	s_cselect_b64 s[18:19], -1, 0
	s_and_b64 s[20:21], s[18:19], exec
	s_cselect_b32 s21, s27, s37
	s_cselect_b32 s20, s26, s36
	s_cselect_b32 s92, s22, s92
	s_cselect_b32 s93, s23, s93
	s_add_i32 s10, s5, s56
	s_add_u32 s11, s7, s66
	s_addc_u32 s26, s24, s67
	s_add_u32 s27, s12, s78
	s_addc_u32 s36, s13, 0
	s_mov_b32 m0, s38
	s_cmpk_lt_u32 s33, 0xa00
	global_load_lds_dwordx4 v48, s[20:21]
	s_cselect_b64 s[20:21], -1, 0
	s_and_b64 s[22:23], s[20:21], exec
	s_cselect_b32 s23, s42, s50
	s_cselect_b32 s22, s39, s43
	s_cselect_b32 s95, s26, s36
	s_cselect_b32 s94, s11, s27
	s_add_i32 s11, s5, s66
	s_add_u32 s36, s7, s68
	s_addc_u32 s37, s24, s69
	s_add_u32 s38, s12, s80
	s_addc_u32 s39, s13, 0
	s_mov_b32 m0, s51
	s_cmpk_lt_u32 s33, 0x800
	global_load_lds_dwordx4 v48, s[22:23]
	s_cselect_b64 s[22:23], -1, 0
	s_and_b64 s[26:27], s[22:23], exec
	s_cselect_b32 s27, s89, s96
	s_cselect_b32 s26, s57, s91
	s_mov_b32 m0, s97
	s_cselect_b32 s96, s36, s38
	s_cselect_b32 s97, s37, s39
	s_add_i32 s89, s5, s68
	s_add_u32 s38, s7, s73
	s_addc_u32 s39, s24, s75
	s_add_u32 s42, s12, s82
	s_addc_u32 s43, s13, 0
	s_cmpk_lt_u32 s33, 0x600
	global_load_lds_dwordx4 v48, s[26:27]
	s_cselect_b64 s[26:27], -1, 0
	s_and_b64 s[36:37], s[26:27], exec
	s_cselect_b32 s37, vcc_hi, s44
	s_cselect_b32 s36, vcc_lo, s76
	s_cselect_b32 vcc_hi, s39, s43
	s_cselect_b32 vcc_lo, s38, s42
	s_add_i32 s91, s5, s73
	s_add_u32 s42, s7, s79
	s_addc_u32 s43, s24, s81
	s_add_u32 s44, s12, s84
	s_mov_b32 m0, s45
	s_addc_u32 s45, s13, 0
	s_cmpk_lt_u32 s33, 0x400
	global_load_lds_dwordx4 v48, s[36:37]
	s_cselect_b64 s[36:37], -1, 0
	s_and_b64 s[38:39], s[36:37], exec
	s_cselect_b32 s39, s46, s86
	s_cselect_b32 s38, s87, s47
	s_mov_b32 m0, s8
	s_cselect_b32 s50, s42, s44
	s_cselect_b32 s51, s43, s45
	s_add_i32 s8, s5, s79
	s_add_u32 s44, s7, s83
	s_addc_u32 s24, s24, s85
	s_add_u32 s45, s12, s88
	s_addc_u32 s46, s13, 0
	s_cmpk_lt_u32 s33, 0x200
	global_load_lds_dwordx4 v48, s[38:39]
	s_cselect_b64 s[38:39], -1, 0
	s_and_b64 s[42:43], s[38:39], exec
	s_cselect_b32 s43, s0, s52
	s_cselect_b32 s42, s9, s1
	s_mov_b32 m0, s53
	global_load_dword v57, v[0:1], off
	s_mov_b32 s7, s3
	global_load_lds_dwordx4 v48, s[42:43]
	s_mov_b32 m0, s14
	s_mov_b32 s57, s3
	global_load_lds_dwordx4 v48, s[58:59]
	s_mov_b32 m0, s15
	v_or_b32_e32 v0, s54, v48
	global_load_lds_dwordx4 v48, s[60:61]
	s_mov_b32 m0, s25
	v_mov_b32_e32 v1, s55
	global_load_lds_dwordx4 v48, s[62:63]
	s_mov_b32 m0, s10
	v_lshl_add_u64 v[2:3], v[0:1], 0, s[6:7]
	global_load_lds_dwordx4 v48, s[92:93]
	s_mov_b32 m0, s11
	v_lshl_add_u64 v[0:1], v[0:1], 0, s[56:57]
	global_load_lds_dwordx4 v48, s[94:95]
	s_mov_b32 m0, s89
	v_readlane_b32 s7, v233, 38
	global_load_lds_dwordx4 v48, s[96:97]
	s_mov_b32 m0, s91
	s_mov_b64 s[42:43], 0x4000
	global_load_lds_dwordx4 v48, vcc
	s_mov_b32 m0, s8
	v_mov_b32_e32 v4, v49
	global_load_lds_dwordx4 v48, s[50:51]
	s_cselect_b32 s51, s24, s46
	s_cselect_b32 s50, s44, s45
	s_add_i32 m0, s5, s83
	s_mov_b32 s44, s90
	global_load_lds_dwordx4 v48, s[50:51]
	s_add_u32 s50, s12, s6
	s_addc_u32 s51, s13, 0
	s_add_i32 m0, s25, 0xe000
	v_mov_b32_e32 v5, v49
	global_load_lds_dwordx4 v48, s[50:51]
	s_add_u32 s50, s12, s56
	s_addc_u32 s51, s13, 0
	s_add_i32 m0, s5, s4
	s_lshl_b32 s5, s90, 11
	global_load_lds_dwordx4 v48, s[50:51]
	s_add_u32 s0, s71, s6
	s_addc_u32 s1, s70, s65
	s_add_u32 s0, s30, s0
	s_addc_u32 s1, s31, s1
	s_add_u32 s58, s0, 0x1c000
	s_addc_u32 s59, s1, 0
	s_add_u32 s0, s71, s56
	s_addc_u32 s1, s70, s64
	s_add_u32 s0, s30, s0
	s_addc_u32 s1, s31, s1
	s_add_u32 s60, s0, 0x1c000
	s_addc_u32 s61, s1, 0
	s_add_u32 s0, s71, s66
	s_addc_u32 s1, s70, s67
	s_add_u32 s0, s30, s0
	s_addc_u32 s1, s31, s1
	s_add_u32 s62, s0, 0x1c000
	s_addc_u32 s63, s1, 0
	s_add_u32 s0, s71, s68
	s_addc_u32 s1, s70, s69
	s_add_u32 s0, s30, s0
	s_addc_u32 s1, s31, s1
	s_add_u32 s64, s0, 0x1c000
	s_addc_u32 s65, s1, 0
	s_add_u32 s0, s71, s73
	s_addc_u32 s1, s70, s75
	s_add_u32 s0, s30, s0
	s_addc_u32 s1, s31, s1
	s_add_u32 s66, s0, 0x1c000
	s_addc_u32 s67, s1, 0
	s_add_u32 s0, s71, s79
	s_addc_u32 s1, s70, s81
	s_add_u32 s0, s30, s0
	s_addc_u32 s1, s31, s1
	s_add_u32 s68, s0, 0x1c000
	s_addc_u32 s69, s1, 0
	s_add_u32 s0, s71, s83
	s_addc_u32 s1, s70, s85
	s_add_u32 s0, s30, s0
	s_addc_u32 s1, s31, s1
	s_add_u32 s70, s0, 0x1c000
	s_addc_u32 s71, s1, 0
	s_add_u32 s0, s54, s72
	s_addc_u32 s1, s55, 0
	s_add_u32 s72, s0, 0x1c08000
	s_addc_u32 s73, s1, 0
	s_add_u32 s0, s54, s74
	s_addc_u32 s1, s55, 0
	s_add_u32 s74, s0, 0x1c08000
	s_addc_u32 s75, s1, 0
	s_add_u32 s0, s54, s78
	s_addc_u32 s1, s55, 0
	s_add_u32 s78, s0, 0x1c08000
	s_addc_u32 s79, s1, 0
	s_add_u32 s0, s54, s80
	s_addc_u32 s1, s55, 0
	s_add_u32 s80, s0, 0x1c08000
	s_addc_u32 s81, s1, 0
	s_add_u32 s0, s54, s82
	s_addc_u32 s1, s55, 0
	s_add_u32 s82, s0, 0x1c08000
	s_addc_u32 s83, s1, 0
	s_add_u32 s0, s54, s84
	s_addc_u32 s1, s55, 0
	s_add_u32 s84, s0, 0x1c08000
	s_addc_u32 s85, s1, 0
	s_add_u32 s0, s54, s88
	s_addc_u32 s1, s55, 0
	s_add_u32 s88, s0, 0x1c08000
	s_addc_u32 s89, s1, 0
	s_and_b32 s0, s2, 3
	s_lshl_b32 s0, s0, 9
	s_and_b32 s1, s33, 0xffffffc0
	s_add_u32 s0, s1, s0
	s_mov_b64 s[50:51], 0x1c08000
	s_addc_u32 s1, 0, 0
	v_lshl_add_u64 v[50:51], v[2:3], 0, s[50:51]
	v_lshl_add_u64 v[52:53], v[0:1], 0, s[50:51]
	v_lshlrev_b32_e32 v0, 9, v188
	s_add_u32 s50, s0, s7
	s_waitcnt vmcnt(0)
	v_and_b32_e32 v0, 0x6000, v0
	v_mov_b32_e32 v1, v49
	s_addc_u32 s51, s1, 0
	v_lshl_add_u64 v[54:55], s[50:51], 0, v[0:1]
	v_lshl_or_b32 v54, v165, 2, v54
	s_mov_b64 s[54:55], 0
	v_mov_b32_e32 v0, v49
	v_mov_b32_e32 v2, v49
	v_mov_b32_e32 v3, v49
	v_mov_b32_e32 v6, v49
	v_mov_b32_e32 v7, v49
	v_mov_b32_e32 v8, v49
	v_mov_b32_e32 v9, v49
	v_mov_b32_e32 v10, v49
	v_mov_b32_e32 v11, v49
	v_mov_b32_e32 v12, v49
	v_mov_b32_e32 v13, v49
	v_mov_b32_e32 v14, v49
	v_mov_b32_e32 v15, v49
	v_mov_b32_e32 v16, v49
	v_mov_b32_e32 v17, v49
	v_mov_b32_e32 v18, v49
	v_mov_b32_e32 v19, v49
	v_mov_b32_e32 v20, v49
	v_mov_b32_e32 v21, v49
	v_mov_b32_e32 v22, v49
	v_mov_b32_e32 v23, v49
	v_mov_b32_e32 v28, v49
	v_mov_b32_e32 v29, v49
	v_mov_b32_e32 v30, v49
	v_mov_b32_e32 v31, v49
	v_mov_b32_e32 v24, v49
	v_mov_b32_e32 v25, v49
	v_mov_b32_e32 v26, v49
	v_mov_b32_e32 v27, v49
	s_waitcnt vmcnt(0) lgkmcnt(0)
	s_barrier
	s_lshl_b32 s6, s44, 10
	s_mul_i32 s1, s2, 0x1c0000
	s_add_u32 s1, s1, s6
	s_add_u32 s1, s1, 0x1c000
	s_add_u32 s10, s30, s1
	s_addc_u32 s11, s31, 0
	s_lshl_b32 s1, s2, 19
	s_add_u32 s1, s1, s6
	s_add_u32 s1, s1, 0x8000
	s_add_u32 s12, s34, s1
	s_addc_u32 s13, s35, 0
	s_lshr_b32 s1, s2, 2
	s_lshl_b32 s1, s1, 22
	s_add_u32 s1, s1, 0xcc00000
	s_add_u32 s14, s48, s1
	s_addc_u32 s15, s49, 0
	s_and_b32 s0, s2, 3
	s_lshl_b32 s0, s0, 9
	s_lshl_b32 s1, s44, 6
	s_add_i32 s0, s0, s1
	v_lshlrev_b32_e32 v190, 9, v188
	v_and_b32_e32 v190, 0x6000, v190
	v_and_b32_e32 v191, 3, v188
	v_lshl_or_b32 v190, v191, 11, v190
	v_and_b32_e32 v191, 12, v188
	v_lshl_or_b32 v190, v191, 2, v190
	v_add_u32_e32 v190, s0, v190
	v_add_u32_e32 v191, 0x8000, v190
	v_add_u32_e32 v192, 0x10000, v190
	v_add_u32_e32 v193, 0x18000, v190
	s_mov_b32 s16, 0x55555555
	s_mov_b32 s17, 0x55555555
	s_mov_b32 s18, 0xaaaaaaaa
	s_mov_b32 s19, 0xaaaaaaaa
	s_mov_b32 s20, 0x33333333
	s_mov_b32 s21, 0x33333333
	s_mov_b32 s22, 0xcccccccc
	s_mov_b32 s23, 0xcccccccc
	v_add_u32_e32 v181, 0x2000, v48
	v_add_u32_e32 v182, 0x4000, v48
	v_add_u32_e32 v183, 0x6000, v48
	v_add_u32_e32 v184, 0x8000, v48
	v_add_u32_e32 v185, 0xa000, v48
	v_add_u32_e32 v186, 0xc000, v48
	v_mov_b32_e32 v93, v48
	v_add_u32_e32 v94, s5, v161
	s_mov_b32 s3, 0
	s_mov_b32 s8, 0x12000
	s_mov_b32 s9, 0
	ds_read_b128 v[120:123], v93 offset:6144
	ds_read_b128 v[124:127], v93 offset:7168
	ds_read_b128 v[128:131], v93 offset:8192
	ds_read_b128 v[132:135], v93 offset:9216
	ds_read_b128 v[136:139], v93 offset:10240
	ds_read_b128 v[140:143], v93 offset:11264
	ds_read_b128 v[96:99], v93
	ds_read_b128 v[100:103], v93 offset:1024
	ds_read_b128 v[104:107], v93 offset:2048
	ds_read_b128 v[108:111], v93 offset:3072
	ds_read_b128 v[112:115], v93 offset:4096
	ds_read_b128 v[116:119], v93 offset:5120
	ds_read2st64_b64 v[172:175], v94 offset0:112 offset1:113
	ds_read2st64_b64 v[176:179], v94 offset0:114 offset1:115

.LBB0_586:
	s_waitcnt vmcnt(0)
	v_readlane_b32 s52, v233, 36
	v_mov_b32_e32 v170, v56
	v_readlane_b32 s53, v233, 37
	s_waitcnt vmcnt(0) lgkmcnt(0)
	s_barrier
	v_cmp_eq_u32_e32 vcc, 0, v188
	s_and_saveexec_b64 s[6:7], vcc
	s_cbranch_execz .Lscan_sig_done
	buffer_wbl2 sc1
	s_waitcnt vmcnt(0)
	v_mov_b32_e32 v0, 0xc000
	v_mov_b32_e32 v1, 1
	global_atomic_add v0, v1, s[48:49]
	s_waitcnt vmcnt(0)
.Lscan_sig_done:
	s_or_b64 exec, exec, s[6:7]
.LBB0_587:
	v_lshrrev_b32_e32 v0, 4, v218
	v_lshlrev_b32_e32 v160, 2, v0
	v_lshrrev_b32_e32 v2, 2, v188
	s_lshl_b32 s0, s44, 13
	v_and_or_b32 v2, v2, 3, v160
	v_lshlrev_b32_e32 v3, 3, v188
	s_add_i32 s0, s0, 0
	v_mul_u32_u24_e32 v2, 0x90, v2
	v_and_b32_e32 v3, 24, v3
	v_lshrrev_b32_e32 v1, 5, v218
	s_movk_i32 s1, 0x90
	v_add3_u32 v171, s0, v2, v3
	v_lshlrev_b32_e32 v0, 3, v0
	v_mov_b32_e32 v2, s0
	v_lshlrev_b32_e32 v164, 3, v1
	v_mad_u32_u24 v2, v170, s1, v2
	v_lshlrev_b32_e32 v1, 4, v1
	v_lshlrev_b32_e32 v162, 1, v0
	v_mbcnt_lo_u32_b32 v0, -1, 0
	s_mov_b32 s17, 0
	s_getreg_b32 s3, hwreg(HW_REG_XCC_ID, 0, 4)
	v_cmp_eq_u32_e64 s[6:7], 0, v218
	v_lshlrev_b32_e32 v172, 4, v165
	v_mov_b32_e32 v163, 0
	v_or_b32_e32 v173, 16, v165
	v_or_b32_e32 v174, 2, v160
	v_or_b32_e32 v175, 3, v160
	v_or_b32_e32 v176, 16, v160
	v_or_b32_e32 v177, 17, v160
	v_or_b32_e32 v178, 18, v160
	v_or_b32_e32 v179, 19, v160
	s_movk_i32 s4, 0x1c00
	s_mov_b64 s[18:19], 0x1000
	s_movk_i32 s5, 0x1000
	s_mov_b32 s54, 0x8000
	s_mov_b32 s55, 0xf000
	s_mov_b32 s56, 0x16000
	s_mov_b64 s[20:21], 0x1400
	s_mov_b64 s[22:23], 0x1800
	v_add_u32_e32 v180, v2, v1
	s_movk_i32 s57, 0x81
	s_mov_b32 s58, 0xff800000
	s_movk_i32 s59, 0xff7e
	s_mov_b64 s[26:27], 0xac00400
	s_mov_b32 s60, 0xac00000
	s_mov_b32 s61, 0xac02000
	s_mov_b32 s62, 0xac04000
	s_mov_b32 s63, 0xac06000
	v_mov_b32_e32 v181, 0xff800000
	v_mbcnt_hi_u32_b32 v182, -1, v0
	s_mov_b32 s64, 0
	s_branch .LBB0_591

.LBB0_626:
	s_waitcnt vmcnt(0)
	v_readlane_b32 s0, v233, 9
	v_readlane_b32 s1, v233, 10
	s_barrier
	s_and_saveexec_b64 s[6:7], s[0:1]
	s_cbranch_execz .LBB0_678
	v_mov_b32_e32 v0, 0xc000
	s_mov_b32 s3, 0
.Lgn_wait:
	global_load_dword v1, v0, s[48:49] sc1
	s_waitcnt vmcnt(0)
	v_readfirstlane_b32 s0, v1
	s_add_u32 s3, s3, 1
	s_nop 3
	s_cmp_ge_u32 s0, 32
	s_cbranch_scc1 .Lgn_ready
	s_sleep 1
	s_cmp_lt_u32 s3, 0x40000
	s_cbranch_scc1 .Lgn_wait
.Lgn_ready:
	buffer_inv sc1
	s_waitcnt vmcnt(0)
.LBB0_678:
	s_or_b64 exec, exec, s[6:7]
	s_lshl_b32 s0, s2, 3
	s_add_i32 s3, s44, s0
	s_cmp_gt_i32 s3, 0xffff
	s_waitcnt lgkmcnt(0)
	s_barrier
	s_cbranch_scc1 .LBB0_689
	v_readlane_b32 s4, v233, 11
	v_readlane_b32 s16, v233, 23
	v_readlane_b32 s17, v233, 24
	v_readlane_b32 s0, v233, 0
	v_readlane_b32 s1, v233, 1
	s_load_dword s66, s[0:1], 0x88
	v_readlane_b32 s5, v233, 12
	v_readlane_b32 s9, v233, 16
	global_load_dwordx2 v[0:1], v161, s[16:17]
	s_add_u32 s4, s48, 0xcc00000
	v_lshlrev_b32_e32 v2, 1, v218
	v_mov_b32_e32 v3, 0
	s_mov_b32 s5, 0x3c00000
	v_mov_b32_e32 v20, 0x358637bd
	s_addc_u32 s56, s49, 0
	s_lshl_b32 s57, s3, 7
	v_lshlrev_b32_e32 v21, 2, v2
	v_lshlrev_b32_e32 v2, 1, v2
	s_waitcnt lgkmcnt(0)
	s_lshl_b32 s58, s66, 3
	s_lshl_b32 s59, s66, 6
	s_lshl_b32 s60, s66, 13
	s_lshl_b32 s61, s66, 4
	s_mul_i32 s62, s66, 24
	s_lshl_b32 s63, s66, 5
	s_mul_i32 s64, s66, 40
	s_mul_i32 s65, s66, 48
	s_mul_i32 s66, s66, 56
	s_mov_b32 s67, 0x800000
	v_readlane_b32 s9, v233, 33
	v_readlane_b32 s6, v233, 13
	v_readlane_b32 s7, v233, 14
	v_readlane_b32 s8, v233, 15
	v_readlane_b32 s10, v233, 17
	v_readlane_b32 s11, v233, 18
	v_readlane_b32 s12, v233, 19
	v_readlane_b32 s13, v233, 20
	v_readlane_b32 s14, v233, 21
	v_readlane_b32 s15, v233, 22
	v_readlane_b32 s18, v233, 25
	v_readlane_b32 s19, v233, 26
	s_waitcnt vmcnt(0)
	v_mov_b32_e32 v5, v0
	s_branch .LBB0_681
